# baseline (speedup 1.0000x reference)
; __device__ __forceinline__ int tidx() { int t = threadIdx.x; asm volatile("" : "+v"(t)); return t; }
; __device__ __forceinline__ int bidx() { int t = blockIdx.x; asm volatile("" : "+s"(t)); return t; }
; template <int EQK, int EV, bool PF, class KP, class SC>
; __device__ __forceinline__ void flash_core(f16v (&o)[EV / 32], float& m_run, float& l_run, const h8 (&qf)[EQK / 16],
;                                            int kt0, int kt1, const KP& kp, const SC& sc, char* smem) {
;     ...
;   auto gload = [&](int kt) {
; #pragma unroll
;     for (int i = 0; i < NKC; ++i) { int c = tid + 256 * i, row = c / KCH, kc = (c - row * KCH) * 8; rk[i] = *(const h8*)(kp.kptr(kt, row) + kc); }
; #pragma unroll
;     for (int i = 0; i < NVC; ++i) { int c = tid + 256 * i, e = c >> 3, kc = (c & 7) * 8; rv[i] = *(const h8*)(kp.vptr(kt, e) + kc); }
;   };
; __device__ __forceinline__ void diff_attn_phase(const P& p_, int j, float lam_init, char* smem, bool dry = false) {
;     ...
;   for (int item = bidx(); item < 1024; item += gridDim.x) {
;     const int b = item >> 8, h = (item >> 5) & 7, qt = item & 31;
;     const int tok = b * S_ + qt * 128 + qslot;
;     f16v o[4];
;     h16* stash = (h16*)(p.ws + S_STASH) + ((size_t)bidx() * 256 + tidx()) * 64;
; #pragma unroll
;     for (int c = 0; c < 2; ++c) {
;       h8 qf[4];
; #pragma unroll
;       for (int d = 0; d < 4; ++d) qf[d] = *(const h8*)(QK + (size_t)tok * 2048 + h * 128 + c * 64 + d * 16 + hi * 8) * (h16)0.125f;
; #pragma unroll
;       for (int et = 0; et < 4; ++et)
; #pragma unroll
;         for (int r = 0; r < 16; ++r) o[et][r] = 0.f;
;       float m_run = -1e30f, l_run = 0.f;
;       KPDiff kp{QK + (size_t)b * S_ * 2048 + 1024 + h * 128 + c * 64, VT + (size_t)(h * 128) * T_ + b * S_};
;       SCDiff sc{exp2f(-(float)(h + 1)), qt * 128};
;       flash_core<64, 128, true>(o, m_run, l_run, qf, 0, 64, kp, sc, smem);
.LBB0_1095:
	v_bfe_u32 v253, v180, 5, 1
	v_lshlrev_b32_e32 v253, 3, v253
	v_and_b32_e32 v252, 1, v180
	v_lshlrev_b32_e32 v252, 3, v252
	v_sub_u32_e32 v252, 0x2400, v252
	s_and_b32 s2, s0, 7
	s_lshl_b32 s2, s2, 6
	s_bfe_u32 s15, s0, 0x60003
	s_or_b32 s2, s2, s15
	s_and_b32 s15, s0, 0x200
	s_or_b32 s2, s2, s15
	s_ashr_i32 s14, s2, 8
	s_lshl_b32 s15, s2, 7
	s_lshl_b32 s16, s14, 12
	s_and_b32 s47, s15, 0xf80
	s_or_b32 s15, s16, s47
	v_add_u32_e32 v140, s15, v169
	v_ashrrev_i32_e32 v141, 31, v140
	s_bfe_u32 s2, s2, 0x30005
	v_lshlrev_b64 v[2:3], 12, v[140:141]
	s_lshl_b32 s88, s2, 8
	v_lshl_add_u64 v[2:3], s[10:11], 0, v[2:3]
	v_lshl_add_u64 v[2:3], v[2:3], 0, s[88:89]
	v_mov_b32_e32 v137, v1
	s_mov_b32 s40, s86
	v_mov_b32_e32 v142, v180
	v_lshl_add_u64 v[144:145], v[2:3], 0, v[136:137]
	s_ashr_i32 s15, s14, 31
	v_mov_b32_e32 v0, v180
	s_mov_b32 s48, s47
	s_lshl_b32 s33, s2, 22
	s_lshl_b32 s46, s2, 7
	s_lshl_b64 s[14:15], s[14:15], 24
	global_load_dwordx4 v[2:5], v[144:145], off
	global_load_dwordx4 v[6:9], v[144:145], off offset:32
	global_load_dwordx4 v[10:13], v[144:145], off offset:64
	global_load_dwordx4 v[14:17], v[144:145], off offset:96
	s_add_u32 s17, s10, s14
	v_add_u32_e32 v28, 0x100, v0
	v_ashrrev_i32_e32 v18, 31, v0
	v_ashrrev_i32_e32 v20, 31, v28
	s_addc_u32 s24, s11, s15
	v_lshrrev_b32_e32 v18, 29, v18
	v_lshrrev_b32_e32 v20, 29, v20
	s_add_u32 s34, s17, s88
	v_add_u32_e32 v18, v0, v18
	v_add_u32_e32 v20, v28, v20
	s_addc_u32 s35, s24, 0
	v_ashrrev_i32_e32 v42, 3, v18
	v_ashrrev_i32_e32 v50, 3, v20
	s_add_u32 s24, s1, s33
	v_lshlrev_b32_e32 v18, 6, v42
	v_lshlrev_b32_e32 v26, 3, v0
	v_lshlrev_b32_e32 v20, 6, v50
	v_lshlrev_b32_e32 v21, 3, v28
	s_addc_u32 s25, s4, 0
	s_ashr_i32 s17, s16, 31
	v_sub_u32_e32 v44, v26, v18
	v_ashrrev_i32_e32 v43, 31, v42
	v_sub_u32_e32 v52, v21, v20
	v_ashrrev_i32_e32 v51, 31, v50
	s_lshl_b64 s[16:17], s[16:17], 1
	v_lshlrev_b64 v[46:47], 12, v[42:43]
	v_ashrrev_i32_e32 v45, 31, v44
	v_lshlrev_b64 v[54:55], 12, v[50:51]
	v_ashrrev_i32_e32 v53, 31, v52
	v_ashrrev_i32_e32 v58, 3, v0
	v_ashrrev_i32_e32 v62, 3, v28
	v_add_u32_e32 v34, 0x200, v0
	s_add_u32 s24, s24, s16
	v_lshl_add_u64 v[18:19], s[34:35], 0, v[46:47]
	v_lshlrev_b64 v[48:49], 1, v[44:45]
	v_lshl_add_u64 v[20:21], s[34:35], 0, v[54:55]
	v_lshlrev_b64 v[56:57], 1, v[52:53]
	v_ashrrev_i32_e32 v59, 31, v58
	v_ashrrev_i32_e32 v63, 31, v62
	v_ashrrev_i32_e32 v66, 3, v34
	v_add_u32_e32 v38, 0x300, v0
	s_addc_u32 s25, s25, s17
	v_lshl_add_u64 v[18:19], v[18:19], 0, v[48:49]
	v_lshl_add_u64 v[22:23], v[20:21], 0, v[56:57]
	v_and_b32_e32 v29, 56, v26
	v_lshlrev_b64 v[60:61], 15, v[58:59]
	v_lshlrev_b64 v[64:65], 15, v[62:63]
	v_ashrrev_i32_e32 v67, 31, v66
	v_ashrrev_i32_e32 v70, 3, v38
	s_barrier
; template <int EQK, int EV, bool PF, class KP, class SC>
; __device__ __forceinline__ void flash_core(f16v (&o)[EV / 32], float& m_run, float& l_run, const h8 (&qf)[EQK / 16],
;                                            int kt0, int kt1, const KP& kp, const SC& sc, char* smem) {
;     ...
;   auto lstore = [&](int buf) {
;     h16* sK = base + buf * BUFH; h16* sV = sK + 64 * KLD;
; #pragma unroll
;     for (int i = 0; i < NKC; ++i) { int c = tid + 256 * i, row = c / KCH, kc = (c - row * KCH) * 8; *(h8*)(sK + row * KLD + kc) = rk[i]; }
; #pragma unroll
;     for (int i = 0; i < NVC; ++i) { int c = tid + 256 * i, e = c >> 3, kc = (c & 7) * 8; *(h8*)(sV + e * VLD + kc) = rv[i]; }
;   };
;   __syncthreads();
;   gload(kt0); lstore(0);
;   __syncthreads();
; __device__ __forceinline__ void diff_attn_phase(const P& p_, int j, float lam_init, char* smem, bool dry = false) {
;     ...
;       h8 qf[4];
; #pragma unroll
;       for (int d = 0; d < 4; ++d) qf[d] = *(const h8*)(QK + (size_t)tok * 2048 + h * 128 + c * 64 + d * 16 + hi * 8) * (h16)0.125f;
; #pragma unroll
;       for (int et = 0; et < 4; ++et)
; #pragma unroll
;         for (int r = 0; r < 16; ++r) o[et][r] = 0.f;
;       float m_run = -1e30f, l_run = 0.f;
;       KPDiff kp{QK + (size_t)b * S_ * 2048 + 1024 + h * 128 + c * 64, VT + (size_t)(h * 128) * T_ + b * S_};
;       SCDiff sc{exp2f(-(float)(h + 1)), qt * 128};
;       flash_core<64, 128, true>(o, m_run, l_run, qf, 0, 64, kp, sc, smem);
	global_load_dwordx4 v[18:21], v[18:19], off offset:2048
	s_nop 0
	global_load_dwordx4 v[22:25], v[22:23], off offset:2048
	v_lshl_add_u64 v[26:27], s[24:25], 0, v[60:61]
	v_lshlrev_b32_e32 v146, 1, v29
	v_mov_b32_e32 v147, v1
	v_lshl_add_u64 v[28:29], s[24:25], 0, v[64:65]
	v_lshlrev_b64 v[68:69], 15, v[66:67]
	v_ashrrev_i32_e32 v71, 31, v70
	v_lshl_add_u64 v[26:27], v[26:27], 0, v[146:147]
	v_lshl_add_u64 v[30:31], v[28:29], 0, v[146:147]
	v_lshl_add_u64 v[34:35], s[24:25], 0, v[68:69]
	v_lshlrev_b64 v[72:73], 15, v[70:71]
	global_load_dwordx4 v[26:29], v[26:27], off
	s_nop 0
	global_load_dwordx4 v[30:33], v[30:31], off
	v_lshl_add_u64 v[34:35], v[34:35], 0, v[146:147]
	v_lshl_add_u64 v[38:39], s[24:25], 0, v[72:73]
	global_load_dwordx4 v[34:37], v[34:35], off
	v_lshl_add_u64 v[38:39], v[38:39], 0, v[146:147]
	global_load_dwordx4 v[38:41], v[38:39], off
	s_add_i32 s2, s2, 1
	v_cvt_f32_ubyte0_e32 v43, s2
	s_mov_b32 s2, 0x42fc0000
	v_cmp_lt_f32_e32 vcc, s2, v43
	s_movk_i32 s3, 0x3000
	v_lshlrev_b32_e32 v173, 1, v44
	v_cndmask_b32_e32 v45, 0, v227, vcc
	s_waitcnt vmcnt(9)
	v_pk_mul_f16 v127, v5, s3 op_sel_hi:[1,0]
	v_pk_mul_f16 v126, v4, s3 op_sel_hi:[1,0]
	v_pk_mul_f16 v125, v3, s3 op_sel_hi:[1,0]
	v_pk_mul_f16 v124, v2, s3 op_sel_hi:[1,0]
	s_waitcnt vmcnt(8)
	v_pk_mul_f16 v123, v9, s3 op_sel_hi:[1,0]
	v_pk_mul_f16 v122, v8, s3 op_sel_hi:[1,0]
	v_pk_mul_f16 v121, v7, s3 op_sel_hi:[1,0]
	v_pk_mul_f16 v120, v6, s3 op_sel_hi:[1,0]
	s_waitcnt vmcnt(7)
	v_pk_mul_f16 v119, v13, s3 op_sel_hi:[1,0]
	v_pk_mul_f16 v118, v12, s3 op_sel_hi:[1,0]
	v_pk_mul_f16 v117, v11, s3 op_sel_hi:[1,0]
	v_pk_mul_f16 v116, v10, s3 op_sel_hi:[1,0]
	s_waitcnt vmcnt(6)
	v_pk_mul_f16 v115, v17, s3 op_sel_hi:[1,0]
	v_pk_mul_f16 v114, v16, s3 op_sel_hi:[1,0]
	v_pk_mul_f16 v113, v15, s3 op_sel_hi:[1,0]
	v_pk_mul_f16 v112, v14, s3 op_sel_hi:[1,0]
	s_movk_i32 s3, 0x48
	v_sub_f32_e32 v43, v45, v43
	v_ashrrev_i32_e32 v3, 1, v0
	v_mul_lo_u32 v172, v42, s3
	v_exp_f32_e32 v43, v43
	v_and_b32_e32 v171, 0xffffffe0, v3
	v_lshl_add_u32 v3, v172, 1, v173
	v_mul_lo_u32 v174, v50, s3
	v_lshlrev_b32_e32 v175, 1, v52
	v_mul_lo_u32 v182, v58, s3
	s_and_b64 s[36:37], vcc, exec
	v_mul_lo_u32 v183, v62, s3
	s_cselect_b32 s36, 0xffffffc0, 0
	v_bfe_u32 v2, v0, 5, 1
	v_mul_lo_u32 v184, v66, s3
	v_ldexp_f32 v137, v43, s36
	v_and_b32_e32 v170, 31, v0
	v_mul_lo_u32 v185, v70, s3
	v_lshlrev_b32_e32 v16, 3, v2
	v_lshlrev_b32_e32 v147, 2, v2
	v_add_u32_e32 v2, s48, v171
	s_add_u32 s36, s33, 0xd100080
	v_or_b32_e32 v2, v2, v170
	s_addc_u32 s37, 0, 0
	v_lshlrev_b32_e32 v0, 4, v0
	v_sub_u32_e32 v187, v2, v147
	v_and_b32_e32 v0, 0x70, v0
	s_add_u32 s52, s14, 0x9140800
	s_addc_u32 s53, s15, 0
	v_mov_b32_e32 v14, v1
	v_mov_b32_e32 v15, v1
	v_mov_b32_e32 v4, v1
	v_mov_b32_e32 v5, v1
	v_mov_b32_e32 v6, v1
	v_mov_b32_e32 v7, v1
	v_mov_b32_e32 v8, v1
	v_mov_b32_e32 v9, v1
	v_mov_b32_e32 v10, v1
	v_mov_b32_e32 v11, v1
	s_waitcnt vmcnt(5)
	ds_write_b128 v3, v[18:21]
	v_lshl_add_u32 v3, v174, 1, v175
	s_waitcnt vmcnt(4)
	ds_write_b128 v3, v[22:25]
	v_lshl_add_u32 v3, v182, 1, v146
	v_mov_b32_e32 v12, v1
	v_mov_b32_e32 v13, v1
	v_lshlrev_b32_e32 v188, 1, v16
	s_mov_b32 s2, 0
	v_mul_u32_u24_e32 v143, 0x48, v170
	v_mul_u32_u24_e32 v139, 0x90, v170
	v_mov_b32_e32 v186, 0xf149f2ca
	s_waitcnt vmcnt(3)
	v_add_u32_e32 v254, v252, v3
	ds_write2_b64 v254, v[26:27], v[28:29] offset1:2
	v_lshl_add_u32 v3, v183, 1, v146
	s_waitcnt vmcnt(2)
	v_add_u32_e32 v255, v252, v3
	ds_write2_b64 v255, v[30:31], v[32:33] offset1:2
	v_lshl_add_u32 v3, v184, 1, v146
	s_waitcnt vmcnt(1)
	v_add_u32_e32 v254, v252, v3
	ds_write2_b64 v254, v[34:35], v[36:37] offset1:2
	v_lshl_add_u32 v3, v185, 1, v146
	s_waitcnt vmcnt(0)
	v_add_u32_e32 v255, v252, v3
	ds_write2_b64 v255, v[38:39], v[40:41] offset1:2
	v_lshl_add_u32 v210, v172, 1, v173
	v_lshl_add_u32 v211, v174, 1, v175
	v_lshl_add_u32 v212, v182, 1, v146
	v_add_u32_e32 v212, v252, v212
	v_lshl_add_u32 v213, v183, 1, v146
	v_add_u32_e32 v213, v252, v213
	v_lshl_add_u32 v214, v184, 1, v146
	v_add_u32_e32 v214, v252, v214
	v_lshl_add_u32 v215, v185, 1, v146
	v_add_u32_e32 v215, v252, v215
	v_lshl_add_u32 v216, v147, 1, v139
	v_add_u32_e32 v216, v253, v216
	v_lshl_add_u64 v[2:3], s[36:37], 0, v[72:73]
	v_or_b32_e32 v2, v2, v0
	v_lshl_add_u64 v[148:149], v[2:3], 0, s[16:17]
	v_lshl_add_u64 v[2:3], s[36:37], 0, v[68:69]
	v_or_b32_e32 v2, v2, v0
	v_lshl_add_u64 v[150:151], v[2:3], 0, s[16:17]
	v_lshl_add_u64 v[2:3], s[36:37], 0, v[64:65]
	v_or_b32_e32 v2, v2, v0
	v_lshl_add_u64 v[152:153], v[2:3], 0, s[16:17]
	v_lshl_add_u64 v[2:3], s[36:37], 0, v[60:61]
	v_or_b32_e32 v2, v2, v0
	v_lshl_add_u64 v[154:155], v[2:3], 0, s[16:17]
	v_lshl_add_u64 v[2:3], s[52:53], 0, v[54:55]
	v_or_b32_e32 v2, s88, v2
	v_lshl_add_u64 v[156:157], v[2:3], 0, v[56:57]
	v_lshl_add_u64 v[2:3], s[52:53], 0, v[46:47]
	v_or_b32_e32 v2, s88, v2
	v_lshl_add_u64 v[158:159], v[2:3], 0, v[48:49]
	v_mov_b32_e32 v0, v1
	v_mov_b32_e32 v2, v1
	v_mov_b32_e32 v3, v1
	v_mov_b64_e32 v[30:31], v[14:15]
	v_mov_b64_e32 v[46:47], v[14:15]
	v_mov_b64_e32 v[62:63], v[14:15]
	v_mov_b64_e32 v[78:79], v[14:15]
	v_mov_b32_e32 v190, 0
	v_mov_b64_e32 v[28:29], v[12:13]
	v_mov_b64_e32 v[26:27], v[10:11]
	v_mov_b64_e32 v[24:25], v[8:9]
	v_mov_b64_e32 v[22:23], v[6:7]
	v_mov_b64_e32 v[20:21], v[4:5]
	v_mov_b64_e32 v[18:19], v[2:3]
	v_mov_b64_e32 v[16:17], v[0:1]
	v_mov_b64_e32 v[44:45], v[12:13]
	v_mov_b64_e32 v[42:43], v[10:11]
	v_mov_b64_e32 v[40:41], v[8:9]
	v_mov_b64_e32 v[38:39], v[6:7]
	v_mov_b64_e32 v[36:37], v[4:5]
	v_mov_b64_e32 v[34:35], v[2:3]
	v_mov_b64_e32 v[32:33], v[0:1]
	v_mov_b64_e32 v[60:61], v[12:13]
	v_mov_b64_e32 v[58:59], v[10:11]
	v_mov_b64_e32 v[56:57], v[8:9]
	v_mov_b64_e32 v[54:55], v[6:7]
	v_mov_b64_e32 v[52:53], v[4:5]
	v_mov_b64_e32 v[50:51], v[2:3]
	v_mov_b64_e32 v[48:49], v[0:1]
	v_mov_b64_e32 v[76:77], v[12:13]
	v_mov_b64_e32 v[74:75], v[10:11]
	v_mov_b64_e32 v[72:73], v[8:9]
	v_mov_b64_e32 v[70:71], v[6:7]
	v_mov_b64_e32 v[68:69], v[4:5]
	v_mov_b64_e32 v[66:67], v[2:3]
	v_mov_b64_e32 v[64:65], v[0:1]
	s_mov_b32 s33, 0
	s_waitcnt lgkmcnt(0)
	s_barrier

; __device__ __forceinline__ f16v mfma16(h8 a, h8 b, f16v c) { return __builtin_amdgcn_mfma_f32_32x32x16_f16(a, b, c, 0, 0, 0); }
; template <int EQK, int EV, bool PF, class KP, class SC>
; __device__ __forceinline__ void flash_core(f16v (&o)[EV / 32], float& m_run, float& l_run, const h8 (&qf)[EQK / 16],
;                                            int kt0, int kt1, const KP& kp, const SC& sc, char* smem) {
;     ...
;       h8 pf[4];
; #pragma unroll
;       for (int i = 0; i < 8; ++i) { pf[0][i] = (h16)p0[i]; pf[1][i] = (h16)p0[8 + i]; pf[2][i] = (h16)p1[i]; pf[3][i] = (h16)p1[8 + i]; }
; #pragma unroll
;       for (int et = 0; et < EV / 32; ++et) {
;         const h16* vb = sV + (et * 32 + l31) * VLD + hi * 4;
; #pragma unroll
;         for (int ks = 0; ks < 4; ++ks) {
;           h4 lo = *(const h4*)(vb + ks * 16), hh = *(const h4*)(vb + ks * 16 + 8);
;           h8 vf = {lo[0], lo[1], lo[2], lo[3], hh[0], hh[1], hh[2], hh[3]};
;           o[et] = mfma16(vf, pf[ks], o[et]);
;         }
;       }
;     }
;     if (PF) {
;       if (more) lstore(cur ^ 1);
;       __syncthreads();
;       cur ^= 1;
;     } else if (more) {
;       __syncthreads();
;       gload(kt + 1); lstore(0);
;       __syncthreads();
;     }
.LBB0_1098:
	v_cvt_pk_f16_f32 v195, v194, v108
	v_cvt_pk_f16_f32 v194, v193, v102
	v_cvt_pk_f16_f32 v193, v192, v96
	v_cvt_pk_f16_f32 v192, v191, v0
	v_add_u32_e32 v254, s41, v216
	v_cvt_pk_f16_f32 v103, v103, v100
	v_cvt_pk_f16_f32 v100, v95, v14
	v_cvt_pk_f16_f32 v167, v111, v166
	v_cvt_pk_f16_f32 v166, v161, v164
	v_cvt_pk_f16_f32 v164, v101, v106
	v_cvt_pk_f16_f32 v106, v105, v110
	v_cvt_pk_f16_f32 v105, v99, v104
	v_cvt_pk_f16_f32 v104, v97, v98
	ds_read_b128 v[96:99], v254 offset:13824
	s_waitcnt lgkmcnt(0)
	v_mfma_f32_32x32x16_f16 v[48:63], v[96:99], v[192:195], v[48:63]
	ds_read_b128 v[96:99], v254 offset:13856
	v_cvt_pk_f16_f32 v165, v107, v160
	v_cvt_pk_f16_f32 v102, v89, v90
	v_cvt_pk_f16_f32 v101, v15, v88
	v_cvt_pk_f16_f32 v107, v109, v162
	s_waitcnt lgkmcnt(0)
	v_mfma_f32_32x32x16_f16 v[48:63], v[96:99], v[164:167], v[48:63]
	ds_read_b128 v[96:99], v254 offset:13888
	ds_read_b128 v[196:199], v254 offset:9216
	s_xor_b32 s33, s33, 1
	s_mul_i32 s41, s33, 0x6c00
	s_mov_b64 s[8:9], 0x80
	s_waitcnt lgkmcnt(1)
	v_mfma_f32_32x32x16_f16 v[48:63], v[96:99], v[100:103], v[48:63]
	ds_read_b128 v[96:99], v254 offset:13920
	v_add_f32_e32 v14, v92, v91
	v_fmac_f32_e32 v14, v190, v94
	ds_read_b128 v[88:91], v254 offset:18528
	s_sub_i32 s2, s2, 64
	v_add_u32_e32 v148, s8, v148
	v_add_u32_e32 v150, s8, v150
	s_waitcnt lgkmcnt(1)
	v_mfma_f32_32x32x16_f16 v[48:63], v[96:99], v[104:107], v[48:63]
	ds_read_b128 v[96:99], v254 offset:18432
	v_add_u32_e32 v152, s8, v152
	v_add_u32_e32 v154, s8, v154
	s_mov_b64 s[8:9], 0x40000
	v_add_u32_e32 v156, s8, v156
	v_add_u32_e32 v158, s8, v158
	s_cmpk_lg_i32 s2, 0xf040
	v_mfma_f32_32x32x16_f16 v[64:79], v[196:199], v[192:195], v[64:79]
	ds_read_b128 v[196:199], v254 offset:9248
	s_waitcnt lgkmcnt(1)
	v_mfma_f32_32x32x16_f16 v[32:47], v[96:99], v[192:195], v[32:47]
	ds_read_b128 v[96:99], v254 offset:18464
	s_waitcnt lgkmcnt(1)
	v_mfma_f32_32x32x16_f16 v[64:79], v[196:199], v[164:167], v[64:79]
	ds_read_b128 v[196:199], v254 offset:9280
	s_waitcnt lgkmcnt(1)
	v_mfma_f32_32x32x16_f16 v[32:47], v[96:99], v[164:167], v[32:47]
	ds_read_b128 v[96:99], v254 offset:18496
	s_waitcnt lgkmcnt(1)
	v_mfma_f32_32x32x16_f16 v[64:79], v[196:199], v[100:103], v[64:79]
	ds_read_b128 v[196:199], v254 offset:9312
	s_waitcnt lgkmcnt(1)
	v_mfma_f32_32x32x16_f16 v[32:47], v[96:99], v[100:103], v[32:47]
	ds_read_b128 v[92:95], v254 offset:23040
	ds_read_b128 v[96:99], v254 offset:23072
	ds_read_b128 v[108:111], v254 offset:23104
	ds_read_b128 v[160:163], v254 offset:23136
	v_add_u32_e32 v0, s41, v210
	s_waitcnt vmcnt(5)
	ds_write_b128 v0, v[6:9]
	v_add_u32_e32 v0, s41, v211
	s_waitcnt vmcnt(4)
	ds_write_b128 v0, v[2:5]
	s_waitcnt lgkmcnt(5)
	v_mfma_f32_32x32x16_f16 v[16:31], v[92:95], v[192:195], v[16:31]
	s_waitcnt vmcnt(3)
	v_add_u32_e32 v254, s41, v212
	ds_write2_b64 v254, v[128:129], v[130:131] offset1:2
	s_waitcnt vmcnt(2)
	v_add_u32_e32 v255, s41, v213
	ds_write2_b64 v255, v[10:11], v[12:13] offset1:2
	s_waitcnt lgkmcnt(6)
	v_mfma_f32_32x32x16_f16 v[16:31], v[96:99], v[164:167], v[16:31]
	s_waitcnt vmcnt(1)
	v_add_u32_e32 v254, s41, v214
	ds_write2_b64 v254, v[84:85], v[86:87] offset1:2
	s_waitcnt vmcnt(0)
	v_add_u32_e32 v255, s41, v215
	ds_write2_b64 v255, v[80:81], v[82:83] offset1:2
	s_waitcnt lgkmcnt(0)
	s_barrier
	v_mfma_f32_32x32x16_f16 v[16:31], v[108:111], v[100:103], v[16:31]
	v_mfma_f32_32x32x16_f16 v[64:79], v[196:199], v[104:107], v[64:79]
	v_mfma_f32_32x32x16_f16 v[32:47], v[88:91], v[104:107], v[32:47]
	v_mfma_f32_32x32x16_f16 v[16:31], v[160:163], v[104:107], v[16:31]
	s_cbranch_scc0 .LBB0_1100
	v_mov_b32_e32 v190, v14
	s_branch .LBB0_1096

; __device__ __forceinline__ f16v mfma16(h8 a, h8 b, f16v c) { return __builtin_amdgcn_mfma_f32_32x32x16_f16(a, b, c, 0, 0, 0); }
; template <int EQK, int EV, bool PF, class KP, class SC>
; __device__ __forceinline__ void flash_core(f16v (&o)[EV / 32], float& m_run, float& l_run, const h8 (&qf)[EQK / 16],
;                                            int kt0, int kt1, const KP& kp, const SC& sc, char* smem) {
;     ...
;       h8 pf[4];
; #pragma unroll
;       for (int i = 0; i < 8; ++i) { pf[0][i] = (h16)p0[i]; pf[1][i] = (h16)p0[8 + i]; pf[2][i] = (h16)p1[i]; pf[3][i] = (h16)p1[8 + i]; }
; #pragma unroll
;       for (int et = 0; et < EV / 32; ++et) {
;         const h16* vb = sV + (et * 32 + l31) * VLD + hi * 4;
; #pragma unroll
;         for (int ks = 0; ks < 4; ++ks) {
;           h4 lo = *(const h4*)(vb + ks * 16), hh = *(const h4*)(vb + ks * 16 + 8);
;           h8 vf = {lo[0], lo[1], lo[2], lo[3], hh[0], hh[1], hh[2], hh[3]};
;           o[et] = mfma16(vf, pf[ks], o[et]);
;         }
;       }
; __device__ __forceinline__ void diff_attn_phase(const P& p_, int j, float lam_init, char* smem, bool dry = false) {
;     ...
;       const float inv = 1.f / l_run;
;       if (c == 0) {
; #pragma unroll
;         for (int et = 0; et < 4; ++et)
; #pragma unroll
;           for (int rg = 0; rg < 2; ++rg) {
;             h8 sv;
; #pragma unroll
;             for (int i = 0; i < 8; ++i) sv[i] = (h16)(o[et][rg * 8 + i] * inv);
;             *(h8*)(stash + et * 16 + rg * 8) = sv;
;           }
.LBB0_1102:
	v_lshl_add_u32 v110, v147, 1, s41
	v_add_u32_e32 v110, v253, v110
	v_lshl_add_u32 v101, v143, 1, v110
	v_add_u32_e32 v111, 0x2000, v101
	ds_read_b128 v[102:105], v111 offset:1024
	v_cvt_pk_f16_f32 v109, v85, v87
	v_cvt_pk_f16_f32 v108, v81, v82
	v_cvt_pk_f16_f32 v107, v10, v11
	v_cvt_pk_f16_f32 v106, v6, v7
	v_cvt_pk_f16_f32 v101, v99, v100
	v_cvt_pk_f16_f32 v100, v97, v98
	v_cvt_pk_f16_f32 v99, v93, v94
	v_cvt_pk_f16_f32 v98, v86, v88
	s_waitcnt lgkmcnt(0)
	v_mfma_f32_32x32x16_f16 v[64:79], v[102:105], v[106:109], v[64:79]
	ds_read_b128 v[102:105], v111 offset:1056
	v_cvt_pk_f16_f32 v87, v95, v96
	v_add_u32_e32 v96, v110, v139
	v_cvt_pk_f16_f32 v7, v12, v15
	v_cvt_pk_f16_f32 v6, v8, v9
	v_cvt_pk_f16_f32 v5, v4, v5
	v_cvt_pk_f16_f32 v4, v2, v3
	ds_read_b128 v[8:11], v111 offset:1120
	s_waitcnt lgkmcnt(1)
	v_mfma_f32_32x32x16_f16 v[64:79], v[102:105], v[98:101], v[64:79]
	ds_read_b128 v[102:105], v111 offset:1088
	v_add_u32_e32 v88, 0x3000, v96
	v_cvt_pk_f16_f32 v85, v83, v84
	v_cvt_pk_f16_f32 v84, v13, v80
	ds_read_b128 v[80:83], v88 offset:1536
	v_cvt_pk_f16_f32 v86, v89, v90
	s_ashr_i32 s41, s40, 31
	s_waitcnt lgkmcnt(1)
	v_mfma_f32_32x32x16_f16 v[64:79], v[102:105], v[4:7], v[64:79]
	s_lshl_b64 s[40:41], s[40:41], 15
	v_ashrrev_i32_e32 v143, 31, v142
	s_add_u32 s40, s5, s40
	v_lshlrev_b64 v[2:3], 7, v[142:143]
	s_addc_u32 s41, s26, s41
	v_lshl_add_u64 v[142:143], s[40:41], 0, v[2:3]
	v_add_f32_e32 v2, v91, v92
	v_mfma_f32_32x32x16_f16 v[64:79], v[8:11], v[84:87], v[64:79]
	ds_read_b128 v[8:11], v88 offset:1568
	v_fmac_f32_e32 v2, v14, v0
	v_add_u32_e32 v0, 0x4800, v96
	s_movk_i32 s2, 0x3000
	v_mov_b32_e32 v184, 0xf149f2ca
	v_mov_b32_e32 v189, 0
	s_waitcnt lgkmcnt(1)
	v_mfma_f32_32x32x16_f16 v[48:63], v[80:83], v[106:109], v[48:63]
	ds_read_b128 v[12:15], v88 offset:1600
	ds_read_b128 v[80:83], v88 offset:1632
	ds_read_b128 v[88:91], v0
	ds_read_b128 v[92:95], v0 offset:32
	s_waitcnt lgkmcnt(4)
	v_mfma_f32_32x32x16_f16 v[48:63], v[8:11], v[98:101], v[48:63]
	ds_read_b128 v[8:11], v0 offset:64
	ds_read_b128 v[102:105], v0 offset:96
	v_add_u32_e32 v0, 0x5800, v96
	ds_read_b128 v[110:113], v0 offset:512
	ds_read_b128 v[114:117], v0 offset:544
	ds_read_b128 v[118:121], v0 offset:576
	ds_read_b128 v[122:125], v0 offset:608
	v_div_scale_f32 v0, s[40:41], v2, v2, 1.0
	v_rcp_f32_e32 v3, v0
	s_waitcnt lgkmcnt(0)
	v_mfma_f32_32x32x16_f16 v[48:63], v[12:15], v[4:7], v[48:63]
	s_barrier
	v_fma_f32 v12, -v0, v3, 1.0
	v_fmac_f32_e32 v3, v12, v3
	v_div_scale_f32 v12, vcc, 1.0, v2, 1.0
	v_mul_f32_e32 v13, v12, v3
	v_fma_f32 v14, -v0, v13, v12
	v_mfma_f32_32x32x16_f16 v[32:47], v[88:91], v[106:109], v[32:47]
	v_fmac_f32_e32 v13, v14, v3
	v_fma_f32 v0, -v0, v13, v12
	v_div_fmas_f32 v0, v0, v3, v13
	v_div_fixup_f32 v0, v0, v2, 1.0
	v_mov_b32_e32 v2, v65
	v_mov_b32_e32 v3, v66
	v_pk_mul_f32 v[2:3], v[0:1], v[2:3] op_sel_hi:[0,1]
	v_mfma_f32_32x32x16_f16 v[16:31], v[110:113], v[106:109], v[16:31]
	v_cvt_pk_f16_f32 v13, v2, v3
	v_mov_b32_e32 v2, v67
	v_mov_b32_e32 v3, v68
	v_mul_f32_e64 v2, v0, v2
	v_mul_f32_e64 v3, v0, v3
	v_cvt_pk_f16_f32 v14, v2, v3
	v_mov_b32_e32 v2, v69
	v_mov_b32_e32 v3, v70
	v_mfma_f32_32x32x16_f16 v[32:47], v[92:95], v[98:101], v[32:47]
	v_mul_f32_e64 v2, v0, v2
	v_mul_f32_e64 v3, v0, v3
	v_fma_mixlo_f16 v12, v0, v64, 0
	v_cvt_pk_f16_f32 v2, v2, v3
	v_pack_b32_f16 v12, v12, v13
	v_alignbit_b32 v13, v14, v13, 16
	v_alignbit_b32 v14, v2, v14, 16
	v_lshrrev_b32_e32 v15, 16, v2
	v_mfma_f32_32x32x16_f16 v[48:63], v[80:83], v[84:87], v[48:63]
	v_mov_b32_e32 v2, v73
	v_mov_b32_e32 v3, v74
	v_mul_f32_e64 v2, v0, v2
	v_mul_f32_e64 v3, v0, v3
	v_fma_mixhi_f16 v15, v0, v71, 0
	global_store_dwordx4 v[142:143], v[12:15], off
	s_mov_b64 s[40:41], 0x80
	v_mfma_f32_32x32x16_f16 v[16:31], v[114:117], v[98:101], v[16:31]
	v_mfma_f32_32x32x16_f16 v[32:47], v[8:11], v[4:7], v[32:47]
	v_cvt_pk_f16_f32 v9, v2, v3
	v_mov_b32_e32 v2, v75
	v_mov_b32_e32 v3, v76
	v_mul_f32_e64 v2, v0, v2
	v_mul_f32_e64 v3, v0, v3
	v_cvt_pk_f16_f32 v10, v2, v3
	v_mov_b32_e32 v2, v77
	v_mov_b32_e32 v3, v78
	v_mfma_f32_32x32x16_f16 v[16:31], v[118:121], v[4:7], v[16:31]
	v_mov_b32_e32 v4, v51
	v_mov_b32_e32 v5, v52
	v_mul_f32_e64 v2, v0, v2
	v_mul_f32_e64 v3, v0, v3
	v_mul_f32_e64 v4, v0, v4
	v_mul_f32_e64 v5, v0, v5
	v_fma_mixlo_f16 v8, v0, v72, 0
	v_cvt_pk_f16_f32 v2, v2, v3
	v_cvt_pk_f16_f32 v6, v4, v5
	v_mov_b32_e32 v4, v53
	v_mov_b32_e32 v5, v54
	v_pack_b32_f16 v8, v8, v9
	v_alignbit_b32 v9, v10, v9, 16
	v_alignbit_b32 v10, v2, v10, 16
	v_lshrrev_b32_e32 v11, 16, v2
	v_mov_b32_e32 v2, v49
	v_mov_b32_e32 v3, v50
	v_pk_mul_f32 v[4:5], v[0:1], v[4:5] op_sel_hi:[0,1]
	v_fma_mixhi_f16 v11, v0, v79, 0
	v_pk_mul_f32 v[2:3], v[0:1], v[2:3] op_sel_hi:[0,1]
	v_cvt_pk_f16_f32 v5, v4, v5
	global_store_dwordx4 v[142:143], v[8:11], off offset:16
	v_cvt_pk_f16_f32 v3, v2, v3
	v_alignbit_b32 v4, v5, v6, 16
	v_fma_mixlo_f16 v8, v0, v48, 0
	v_lshrrev_b32_e32 v5, 16, v5
	v_pack_b32_f16 v2, v8, v3
	v_alignbit_b32 v3, v6, v3, 16
	v_fma_mixhi_f16 v5, v0, v55, 0
	global_store_dwordx4 v[142:143], v[2:5], off offset:32
	v_mfma_f32_32x32x16_f16 v[32:47], v[102:105], v[84:87], v[32:47]
	s_nop 0
	v_mov_b32_e32 v2, v57
	v_mov_b32_e32 v3, v58
	v_mul_f32_e64 v2, v0, v2
	v_mul_f32_e64 v3, v0, v3
	v_fma_mixlo_f16 v4, v0, v56, 0
	v_cvt_pk_f16_f32 v3, v2, v3
	v_pack_b32_f16 v2, v4, v3
	v_mov_b32_e32 v4, v59
	v_mov_b32_e32 v5, v60
	v_pk_mul_f32 v[4:5], v[0:1], v[4:5] op_sel_hi:[0,1]
	v_cvt_pk_f16_f32 v6, v4, v5
	v_mov_b32_e32 v4, v61
	v_mov_b32_e32 v5, v62
	v_pk_mul_f32 v[4:5], v[0:1], v[4:5] op_sel_hi:[0,1]
	v_cvt_pk_f16_f32 v5, v4, v5
	v_alignbit_b32 v4, v5, v6, 16
	v_lshrrev_b32_e32 v5, 16, v5
; __device__ __forceinline__ void diff_attn_phase(const P& p_, int j, float lam_init, char* smem, bool dry = false) {
;     ...
;       h8 qf[4];
; #pragma unroll
;       for (int d = 0; d < 4; ++d) qf[d] = *(const h8*)(QK + (size_t)tok * 2048 + h * 128 + c * 64 + d * 16 + hi * 8) * (h16)0.125f;
;     ...
;       if (c == 0) {
; #pragma unroll
;         for (int et = 0; et < 4; ++et)
; #pragma unroll
;           for (int rg = 0; rg < 2; ++rg) {
;             h8 sv;
; #pragma unroll
;             for (int i = 0; i < 8; ++i) sv[i] = (h16)(o[et][rg * 8 + i] * inv);
;             *(h8*)(stash + et * 16 + rg * 8) = sv;
;           }
	v_alignbit_b32 v3, v6, v3, 16
	v_fma_mixhi_f16 v5, v0, v63, 0
	global_store_dwordx4 v[142:143], v[2:5], off offset:48
	v_mfma_f32_32x32x16_f16 v[16:31], v[122:125], v[84:87], v[16:31]
	s_nop 0
	v_mov_b32_e32 v2, v33
	v_mov_b32_e32 v3, v34
	v_mul_f32_e64 v2, v0, v2
	v_mul_f32_e64 v3, v0, v3
	v_fma_mixlo_f16 v4, v0, v32, 0
	v_cvt_pk_f16_f32 v3, v2, v3
	v_pack_b32_f16 v2, v4, v3
	v_mov_b32_e32 v4, v35
	v_mov_b32_e32 v5, v36
	v_pk_mul_f32 v[4:5], v[0:1], v[4:5] op_sel_hi:[0,1]
	v_cvt_pk_f16_f32 v6, v4, v5
	v_mov_b32_e32 v4, v37
	v_mov_b32_e32 v5, v38
	v_pk_mul_f32 v[4:5], v[0:1], v[4:5] op_sel_hi:[0,1]
	v_cvt_pk_f16_f32 v5, v4, v5
	v_alignbit_b32 v4, v5, v6, 16
	v_lshrrev_b32_e32 v5, 16, v5
	v_alignbit_b32 v3, v6, v3, 16
	v_fma_mixhi_f16 v5, v0, v39, 0
	global_store_dwordx4 v[142:143], v[2:5], off offset:64
	s_nop 1
	v_mov_b32_e32 v2, v41
	v_mov_b32_e32 v3, v42
	v_pk_mul_f32 v[2:3], v[0:1], v[2:3] op_sel_hi:[0,1]
	v_fma_mixlo_f16 v4, v0, v40, 0
	v_cvt_pk_f16_f32 v3, v2, v3
	v_pack_b32_f16 v2, v4, v3
	v_mov_b32_e32 v4, v43
	v_mov_b32_e32 v5, v44
	v_pk_mul_f32 v[4:5], v[0:1], v[4:5] op_sel_hi:[0,1]
	v_cvt_pk_f16_f32 v6, v4, v5
	v_mov_b32_e32 v4, v45
	v_mov_b32_e32 v5, v46
	v_pk_mul_f32 v[4:5], v[0:1], v[4:5] op_sel_hi:[0,1]
	v_cvt_pk_f16_f32 v5, v4, v5
	v_alignbit_b32 v4, v5, v6, 16
	v_lshrrev_b32_e32 v5, 16, v5
	v_alignbit_b32 v3, v6, v3, 16
	v_fma_mixhi_f16 v5, v0, v47, 0
	global_store_dwordx4 v[142:143], v[2:5], off offset:80
	s_nop 1
	v_mov_b32_e32 v2, v17
	v_mov_b32_e32 v3, v18
	v_pk_mul_f32 v[2:3], v[0:1], v[2:3] op_sel_hi:[0,1]
	v_fma_mixlo_f16 v4, v0, v16, 0
	v_cvt_pk_f16_f32 v3, v2, v3
	v_pack_b32_f16 v2, v4, v3
	v_mov_b32_e32 v4, v19
	v_mov_b32_e32 v5, v20
	v_pk_mul_f32 v[4:5], v[0:1], v[4:5] op_sel_hi:[0,1]
	v_cvt_pk_f16_f32 v6, v4, v5
	v_mov_b32_e32 v4, v21
	v_mov_b32_e32 v5, v22
	v_pk_mul_f32 v[4:5], v[0:1], v[4:5] op_sel_hi:[0,1]
	v_cvt_pk_f16_f32 v5, v4, v5
	v_alignbit_b32 v4, v5, v6, 16
	v_lshrrev_b32_e32 v5, 16, v5
	v_alignbit_b32 v3, v6, v3, 16
	v_fma_mixhi_f16 v5, v0, v23, 0
	global_store_dwordx4 v[142:143], v[2:5], off offset:96
	s_nop 1
	v_mov_b32_e32 v2, v25
	v_mov_b32_e32 v3, v26
	v_pk_mul_f32 v[2:3], v[0:1], v[2:3] op_sel_hi:[0,1]
	v_fma_mixlo_f16 v4, v0, v24, 0
	v_cvt_pk_f16_f32 v3, v2, v3
	v_pack_b32_f16 v2, v4, v3
	v_mov_b32_e32 v4, v27
	v_mov_b32_e32 v5, v28
	v_pk_mul_f32 v[4:5], v[0:1], v[4:5] op_sel_hi:[0,1]
	v_cvt_pk_f16_f32 v6, v4, v5
	v_mov_b32_e32 v4, v29
	v_mov_b32_e32 v5, v30
	v_pk_mul_f32 v[4:5], v[0:1], v[4:5] op_sel_hi:[0,1]
	v_cvt_pk_f16_f32 v5, v4, v5
	v_alignbit_b32 v4, v5, v6, 16
	v_lshrrev_b32_e32 v5, 16, v5
	v_alignbit_b32 v3, v6, v3, 16
	v_fma_mixhi_f16 v5, v0, v31, 0
	global_store_dwordx4 v[142:143], v[2:5], off offset:112
	v_mov_b32_e32 v0, v180
	global_load_dwordx4 v[2:5], v[144:145], off offset:224
	global_load_dwordx4 v[6:9], v[144:145], off offset:192
	global_load_dwordx4 v[10:13], v[144:145], off offset:160
	global_load_dwordx4 v[14:17], v[144:145], off offset:128
	s_nop 0
	v_add_u32_e32 v28, 0x100, v0
	v_ashrrev_i32_e32 v18, 31, v0
	v_ashrrev_i32_e32 v20, 31, v28
	v_lshrrev_b32_e32 v18, 29, v18
	v_lshrrev_b32_e32 v20, 29, v20
	v_add_u32_e32 v18, v0, v18
	v_add_u32_e32 v20, v28, v20
	v_ashrrev_i32_e32 v42, 3, v18
	v_ashrrev_i32_e32 v50, 3, v20
	v_lshlrev_b32_e32 v18, 6, v42
	v_lshlrev_b32_e32 v26, 3, v0
	v_lshlrev_b32_e32 v20, 6, v50
	v_lshlrev_b32_e32 v21, 3, v28
	v_sub_u32_e32 v44, v26, v18
	v_ashrrev_i32_e32 v43, 31, v42
	v_sub_u32_e32 v52, v21, v20
	v_ashrrev_i32_e32 v51, 31, v50
	v_lshlrev_b64 v[46:47], 12, v[42:43]
	v_ashrrev_i32_e32 v45, 31, v44
	v_lshlrev_b64 v[54:55], 12, v[50:51]
	v_ashrrev_i32_e32 v53, 31, v52
	v_ashrrev_i32_e32 v58, 3, v0
	v_ashrrev_i32_e32 v62, 3, v28
	v_add_u32_e32 v34, 0x200, v0
	v_lshl_add_u64 v[18:19], s[34:35], 0, v[46:47]
	v_lshlrev_b64 v[48:49], 1, v[44:45]
	v_lshl_add_u64 v[20:21], s[34:35], 0, v[54:55]
	v_lshlrev_b64 v[56:57], 1, v[52:53]
	v_ashrrev_i32_e32 v59, 31, v58
	v_ashrrev_i32_e32 v63, 31, v62
	v_ashrrev_i32_e32 v66, 3, v34
	v_add_u32_e32 v38, 0x300, v0
	v_lshl_add_u64 v[18:19], v[18:19], 0, v[48:49]
	v_lshl_add_u64 v[22:23], v[20:21], 0, v[56:57]
	v_and_b32_e32 v29, 56, v26
	v_lshlrev_b64 v[60:61], 15, v[58:59]
	v_lshlrev_b64 v[64:65], 15, v[62:63]
	v_ashrrev_i32_e32 v67, 31, v66
	v_ashrrev_i32_e32 v70, 3, v38
	s_barrier
; template <int EQK, int EV, bool PF, class KP, class SC>
; __device__ __forceinline__ void flash_core(f16v (&o)[EV / 32], float& m_run, float& l_run, const h8 (&qf)[EQK / 16],
;                                            int kt0, int kt1, const KP& kp, const SC& sc, char* smem) {
;     ...
;   auto lstore = [&](int buf) {
;     h16* sK = base + buf * BUFH; h16* sV = sK + 64 * KLD;
; #pragma unroll
;     for (int i = 0; i < NKC; ++i) { int c = tid + 256 * i, row = c / KCH, kc = (c - row * KCH) * 8; *(h8*)(sK + row * KLD + kc) = rk[i]; }
; #pragma unroll
;     for (int i = 0; i < NVC; ++i) { int c = tid + 256 * i, e = c >> 3, kc = (c & 7) * 8; *(h8*)(sV + e * VLD + kc) = rv[i]; }
;   };
;   __syncthreads();
;   gload(kt0); lstore(0);
;   __syncthreads();
; __device__ __forceinline__ void diff_attn_phase(const P& p_, int j, float lam_init, char* smem, bool dry = false) {
;     ...
;       h8 qf[4];
; #pragma unroll
;       for (int d = 0; d < 4; ++d) qf[d] = *(const h8*)(QK + (size_t)tok * 2048 + h * 128 + c * 64 + d * 16 + hi * 8) * (h16)0.125f;
; #pragma unroll
;       for (int et = 0; et < 4; ++et)
; #pragma unroll
;         for (int r = 0; r < 16; ++r) o[et][r] = 0.f;
;       float m_run = -1e30f, l_run = 0.f;
;       KPDiff kp{QK + (size_t)b * S_ * 2048 + 1024 + h * 128 + c * 64, VT + (size_t)(h * 128) * T_ + b * S_};
;       SCDiff sc{exp2f(-(float)(h + 1)), qt * 128};
;       flash_core<64, 128, true>(o, m_run, l_run, qf, 0, 64, kp, sc, smem);
	global_load_dwordx4 v[18:21], v[18:19], off offset:2176
	s_nop 0
	global_load_dwordx4 v[22:25], v[22:23], off offset:2176
	v_lshl_add_u64 v[26:27], s[24:25], 0, v[60:61]
	v_lshlrev_b32_e32 v144, 1, v29
	v_mov_b32_e32 v145, v1
	v_lshl_add_u64 v[28:29], s[24:25], 0, v[64:65]
	v_lshlrev_b64 v[68:69], 15, v[66:67]
	v_ashrrev_i32_e32 v71, 31, v70
	v_lshl_add_u64 v[26:27], v[26:27], 0, v[144:145]
	v_lshl_add_u64 v[30:31], v[28:29], 0, v[144:145]
	v_lshl_add_u64 v[34:35], s[24:25], 0, v[68:69]
	v_lshlrev_b64 v[72:73], 15, v[70:71]
	global_load_dwordx4 v[26:29], v[26:27], off
	s_nop 0
	global_load_dwordx4 v[30:33], v[30:31], off
	v_lshl_add_u64 v[34:35], v[34:35], 0, v[144:145]
	v_lshl_add_u64 v[38:39], s[24:25], 0, v[72:73]
	global_load_dwordx4 v[34:37], v[34:35], off
	v_lshl_add_u64 v[38:39], v[38:39], 0, v[144:145]
	global_load_dwordx4 v[38:41], v[38:39], off
	v_lshlrev_b32_e32 v172, 1, v44
	v_lshlrev_b32_e32 v174, 1, v52
	v_and_b32_e32 v167, 31, v0
	v_mul_u32_u24_e32 v145, 0x48, v167
	v_mul_u32_u24_e32 v139, 0x90, v167
	s_waitcnt vmcnt(9)
	v_pk_mul_f16 v115, v5, s2 op_sel_hi:[1,0]
	s_waitcnt vmcnt(8)
	v_pk_mul_f16 v119, v9, s2 op_sel_hi:[1,0]
	s_waitcnt vmcnt(7)
	v_pk_mul_f16 v123, v13, s2 op_sel_hi:[1,0]
	s_waitcnt vmcnt(6)
	v_pk_mul_f16 v127, v17, s2 op_sel_hi:[1,0]
	v_pk_mul_f16 v126, v16, s2 op_sel_hi:[1,0]
	v_pk_mul_f16 v125, v15, s2 op_sel_hi:[1,0]
	v_pk_mul_f16 v124, v14, s2 op_sel_hi:[1,0]
	v_pk_mul_f16 v122, v12, s2 op_sel_hi:[1,0]
	v_pk_mul_f16 v121, v11, s2 op_sel_hi:[1,0]
	v_pk_mul_f16 v120, v10, s2 op_sel_hi:[1,0]
	v_pk_mul_f16 v118, v8, s2 op_sel_hi:[1,0]
	v_pk_mul_f16 v117, v7, s2 op_sel_hi:[1,0]
	v_pk_mul_f16 v116, v6, s2 op_sel_hi:[1,0]
	v_pk_mul_f16 v114, v4, s2 op_sel_hi:[1,0]
	v_pk_mul_f16 v113, v3, s2 op_sel_hi:[1,0]
	v_pk_mul_f16 v112, v2, s2 op_sel_hi:[1,0]
	s_movk_i32 s2, 0x48
	v_ashrrev_i32_e32 v3, 1, v0
	v_mul_lo_u32 v171, v42, s2
	v_and_b32_e32 v170, 0xffffffe0, v3
	v_lshl_add_u32 v3, v171, 1, v172
	v_mul_lo_u32 v173, v50, s2
	v_mul_lo_u32 v175, v58, s2
	v_mul_lo_u32 v182, v62, s2
	v_mul_lo_u32 v183, v66, s2
	v_bfe_u32 v2, v0, 5, 1
	v_mul_lo_u32 v185, v70, s2
	v_lshlrev_b32_e32 v16, 3, v2
	v_lshlrev_b32_e32 v166, 2, v2
	v_add3_u32 v2, s48, v170, v167
	v_and_b32_e32 v0, 7, v0
	v_sub_u32_e32 v186, v2, v166
	v_lshlrev_b32_e32 v0, 4, v0
	s_add_u32 s2, s14, s88
	s_addc_u32 s15, s15, 0
	s_add_u32 s14, s2, 0x9140880
	s_addc_u32 s15, s15, 0
	v_mov_b32_e32 v14, v1
	v_mov_b32_e32 v15, v1
	v_mov_b32_e32 v4, v1
	v_mov_b32_e32 v5, v1
	v_mov_b32_e32 v6, v1
	v_mov_b32_e32 v7, v1
	v_mov_b32_e32 v8, v1
	v_mov_b32_e32 v9, v1
	v_mov_b32_e32 v10, v1
	s_waitcnt vmcnt(5)
	ds_write_b128 v3, v[18:21]
	v_lshl_add_u32 v3, v173, 1, v174
	s_waitcnt vmcnt(4)
	ds_write_b128 v3, v[22:25]
	v_lshl_add_u32 v3, v175, 1, v144
	v_mov_b32_e32 v11, v1
	v_mov_b32_e32 v12, v1
	v_mov_b32_e32 v13, v1
	v_lshlrev_b32_e32 v187, 1, v16
	s_mov_b32 s2, 0
	s_waitcnt vmcnt(3)
	v_add_u32_e32 v254, v252, v3
	ds_write2_b64 v254, v[26:27], v[28:29] offset1:2
	v_lshl_add_u32 v3, v182, 1, v144
	s_waitcnt vmcnt(2)
	v_add_u32_e32 v255, v252, v3
	ds_write2_b64 v255, v[30:31], v[32:33] offset1:2
	v_lshl_add_u32 v3, v183, 1, v144
	s_waitcnt vmcnt(1)
	v_add_u32_e32 v254, v252, v3
	ds_write2_b64 v254, v[34:35], v[36:37] offset1:2
	v_lshl_add_u32 v3, v185, 1, v144
	s_waitcnt vmcnt(0)
	v_add_u32_e32 v255, v252, v3
	ds_write2_b64 v255, v[38:39], v[40:41] offset1:2
	v_lshl_add_u32 v210, v171, 1, v172
	v_lshl_add_u32 v211, v173, 1, v174
	v_lshl_add_u32 v212, v175, 1, v144
	v_add_u32_e32 v212, v252, v212
	v_lshl_add_u32 v213, v182, 1, v144
	v_add_u32_e32 v213, v252, v213
	v_lshl_add_u32 v214, v183, 1, v144
	v_add_u32_e32 v214, v252, v214
	v_lshl_add_u32 v215, v185, 1, v144
	v_add_u32_e32 v215, v252, v215
	v_lshl_add_u32 v216, v166, 1, v139
	v_add_u32_e32 v216, v253, v216
	v_lshl_add_u64 v[2:3], s[36:37], 0, v[72:73]
	v_lshl_add_u64 v[2:3], v[2:3], 0, v[0:1]
	v_lshl_add_u64 v[146:147], v[2:3], 0, s[16:17]
	v_lshl_add_u64 v[2:3], s[36:37], 0, v[68:69]
	v_lshl_add_u64 v[2:3], v[2:3], 0, v[0:1]
	v_lshl_add_u64 v[148:149], v[2:3], 0, s[16:17]
	v_lshl_add_u64 v[2:3], s[36:37], 0, v[64:65]
	v_lshl_add_u64 v[2:3], v[2:3], 0, v[0:1]
	v_lshl_add_u64 v[150:151], v[2:3], 0, s[16:17]
	v_lshl_add_u64 v[2:3], s[36:37], 0, v[60:61]
	v_lshl_add_u64 v[2:3], v[2:3], 0, v[0:1]
	v_lshl_add_u64 v[152:153], v[2:3], 0, s[16:17]
	v_lshl_add_u64 v[2:3], s[14:15], 0, v[54:55]
	v_lshl_add_u64 v[154:155], v[2:3], 0, v[56:57]
	v_lshl_add_u64 v[2:3], s[14:15], 0, v[46:47]
	v_lshl_add_u64 v[156:157], v[2:3], 0, v[48:49]
	v_mov_b32_e32 v0, v1
	v_mov_b32_e32 v2, v1
	v_mov_b32_e32 v3, v1
	v_mov_b64_e32 v[30:31], v[14:15]
	v_mov_b64_e32 v[46:47], v[14:15]
	v_mov_b64_e32 v[62:63], v[14:15]
	v_mov_b64_e32 v[78:79], v[14:15]
	v_mov_b64_e32 v[28:29], v[12:13]
	v_mov_b64_e32 v[26:27], v[10:11]
	v_mov_b64_e32 v[24:25], v[8:9]
	v_mov_b64_e32 v[22:23], v[6:7]
	v_mov_b64_e32 v[20:21], v[4:5]
	v_mov_b64_e32 v[18:19], v[2:3]
	v_mov_b64_e32 v[16:17], v[0:1]
	v_mov_b64_e32 v[44:45], v[12:13]
	v_mov_b64_e32 v[42:43], v[10:11]
	v_mov_b64_e32 v[40:41], v[8:9]
	v_mov_b64_e32 v[38:39], v[6:7]
	v_mov_b64_e32 v[36:37], v[4:5]
	v_mov_b64_e32 v[34:35], v[2:3]
	v_mov_b64_e32 v[32:33], v[0:1]
	v_mov_b64_e32 v[60:61], v[12:13]
	v_mov_b64_e32 v[58:59], v[10:11]
	v_mov_b64_e32 v[56:57], v[8:9]
	v_mov_b64_e32 v[54:55], v[6:7]
	v_mov_b64_e32 v[52:53], v[4:5]
	v_mov_b64_e32 v[50:51], v[2:3]
	v_mov_b64_e32 v[48:49], v[0:1]
	v_mov_b64_e32 v[76:77], v[12:13]
	v_mov_b64_e32 v[74:75], v[10:11]
	v_mov_b64_e32 v[72:73], v[8:9]
	v_mov_b64_e32 v[70:71], v[6:7]
	v_mov_b64_e32 v[68:69], v[4:5]
	v_mov_b64_e32 v[66:67], v[2:3]
	v_mov_b64_e32 v[64:65], v[0:1]
	s_mov_b32 s14, 0
	s_waitcnt lgkmcnt(0)
	s_barrier

; __device__ __forceinline__ f16v mfma16(h8 a, h8 b, f16v c) { return __builtin_amdgcn_mfma_f32_32x32x16_f16(a, b, c, 0, 0, 0); }
; template <int EQK, int EV, bool PF, class KP, class SC>
; __device__ __forceinline__ void flash_core(f16v (&o)[EV / 32], float& m_run, float& l_run, const h8 (&qf)[EQK / 16],
;                                            int kt0, int kt1, const KP& kp, const SC& sc, char* smem) {
;     ...
;       h8 pf[4];
; #pragma unroll
;       for (int i = 0; i < 8; ++i) { pf[0][i] = (h16)p0[i]; pf[1][i] = (h16)p0[8 + i]; pf[2][i] = (h16)p1[i]; pf[3][i] = (h16)p1[8 + i]; }
; #pragma unroll
;       for (int et = 0; et < EV / 32; ++et) {
;         const h16* vb = sV + (et * 32 + l31) * VLD + hi * 4;
; #pragma unroll
;         for (int ks = 0; ks < 4; ++ks) {
;           h4 lo = *(const h4*)(vb + ks * 16), hh = *(const h4*)(vb + ks * 16 + 8);
;           h8 vf = {lo[0], lo[1], lo[2], lo[3], hh[0], hh[1], hh[2], hh[3]};
;           o[et] = mfma16(vf, pf[ks], o[et]);
;         }
;       }
;     }
;     if (PF) {
;       if (more) lstore(cur ^ 1);
;       __syncthreads();
;       cur ^= 1;
;     } else if (more) {
;       __syncthreads();
;       gload(kt + 1); lstore(0);
;       __syncthreads();
;     }
.LBB0_1105:
	v_cvt_pk_f16_f32 v190, v190, v0
	v_add_u32_e32 v254, s15, v216
	v_cvt_pk_f16_f32 v103, v103, v100
	v_cvt_pk_f16_f32 v100, v95, v14
	v_cvt_pk_f16_f32 v191, v191, v96
	v_cvt_pk_f16_f32 v165, v111, v164
	v_cvt_pk_f16_f32 v164, v159, v162
	v_cvt_pk_f16_f32 v162, v101, v106
	v_cvt_pk_f16_f32 v106, v105, v110
	v_cvt_pk_f16_f32 v105, v99, v104
	v_cvt_pk_f16_f32 v104, v97, v98
	ds_read_b128 v[96:99], v254 offset:13824
	v_cvt_pk_f16_f32 v193, v193, v108
	v_cvt_pk_f16_f32 v192, v192, v102
	v_cvt_pk_f16_f32 v163, v107, v158
	v_cvt_pk_f16_f32 v102, v89, v90
	s_waitcnt lgkmcnt(0)
	v_mfma_f32_32x32x16_f16 v[48:63], v[96:99], v[190:193], v[48:63]
	ds_read_b128 v[96:99], v254 offset:13856
	v_cvt_pk_f16_f32 v101, v15, v88
	v_cvt_pk_f16_f32 v107, v109, v160
	ds_read_b128 v[194:197], v254 offset:9216
	s_waitcnt lgkmcnt(1)
	v_mfma_f32_32x32x16_f16 v[48:63], v[96:99], v[162:165], v[48:63]
	ds_read_b128 v[96:99], v254 offset:13888
	s_xor_b32 s14, s14, 1
	s_mul_i32 s15, s14, 0x6c00
	s_sub_i32 s2, s2, 64
	s_mov_b64 s[8:9], 0x40000
	v_add_u32_e32 v146, s40, v146
	s_waitcnt lgkmcnt(0)
	v_mfma_f32_32x32x16_f16 v[48:63], v[96:99], v[100:103], v[48:63]
	ds_read_b128 v[96:99], v254 offset:13920
	v_add_f32_e32 v14, v92, v91
	v_fmac_f32_e32 v14, v189, v94
	ds_read_b128 v[88:91], v254 offset:18528
	v_add_u32_e32 v148, s40, v148
	v_add_u32_e32 v150, s40, v150
	v_add_u32_e32 v152, s40, v152
	s_waitcnt lgkmcnt(1)
	v_mfma_f32_32x32x16_f16 v[48:63], v[96:99], v[104:107], v[48:63]
	ds_read_b128 v[96:99], v254 offset:18432
	v_add_u32_e32 v154, s8, v154
	v_add_u32_e32 v156, s8, v156
	s_cmpk_lg_i32 s2, 0xf040
	v_mfma_f32_32x32x16_f16 v[64:79], v[194:197], v[190:193], v[64:79]
	ds_read_b128 v[194:197], v254 offset:9248
	s_waitcnt lgkmcnt(1)
	v_mfma_f32_32x32x16_f16 v[32:47], v[96:99], v[190:193], v[32:47]
	ds_read_b128 v[96:99], v254 offset:18464
	s_waitcnt lgkmcnt(1)
	v_mfma_f32_32x32x16_f16 v[64:79], v[194:197], v[162:165], v[64:79]
	ds_read_b128 v[194:197], v254 offset:9280
	s_waitcnt lgkmcnt(1)
	v_mfma_f32_32x32x16_f16 v[32:47], v[96:99], v[162:165], v[32:47]
	ds_read_b128 v[96:99], v254 offset:18496
	s_waitcnt lgkmcnt(1)
	v_mfma_f32_32x32x16_f16 v[64:79], v[194:197], v[100:103], v[64:79]
	ds_read_b128 v[194:197], v254 offset:9312
	s_waitcnt lgkmcnt(1)
	v_mfma_f32_32x32x16_f16 v[32:47], v[96:99], v[100:103], v[32:47]
	ds_read_b128 v[92:95], v254 offset:23040
	ds_read_b128 v[96:99], v254 offset:23072
	ds_read_b128 v[108:111], v254 offset:23104
	ds_read_b128 v[158:161], v254 offset:23136
	v_add_u32_e32 v0, s15, v210
	s_waitcnt vmcnt(5)
	ds_write_b128 v0, v[6:9]
	v_add_u32_e32 v0, s15, v211
	s_waitcnt vmcnt(4)
	ds_write_b128 v0, v[2:5]
	s_waitcnt lgkmcnt(5)
	v_mfma_f32_32x32x16_f16 v[16:31], v[92:95], v[190:193], v[16:31]
	s_waitcnt vmcnt(3)
	v_add_u32_e32 v254, s15, v212
	ds_write2_b64 v254, v[128:129], v[130:131] offset1:2
	s_waitcnt vmcnt(2)
	v_add_u32_e32 v255, s15, v213
	ds_write2_b64 v255, v[10:11], v[12:13] offset1:2
	s_waitcnt lgkmcnt(6)
	v_mfma_f32_32x32x16_f16 v[16:31], v[96:99], v[162:165], v[16:31]
	s_waitcnt vmcnt(1)
	v_add_u32_e32 v254, s15, v214
	ds_write2_b64 v254, v[84:85], v[86:87] offset1:2
	s_waitcnt vmcnt(0)
	v_add_u32_e32 v255, s15, v215
	ds_write2_b64 v255, v[80:81], v[82:83] offset1:2
	s_waitcnt lgkmcnt(0)
	s_barrier
	v_mfma_f32_32x32x16_f16 v[16:31], v[108:111], v[100:103], v[16:31]
	v_mfma_f32_32x32x16_f16 v[64:79], v[194:197], v[104:107], v[64:79]
	v_mfma_f32_32x32x16_f16 v[32:47], v[88:91], v[104:107], v[32:47]
	v_mfma_f32_32x32x16_f16 v[16:31], v[158:161], v[104:107], v[16:31]
	s_cbranch_scc0 .LBB0_1107
	v_mov_b32_e32 v189, v14
	s_branch .LBB0_1103
